# attn unmasked loop: waves 4-7 staggered half an iteration (mid-iteration barrier), K ds_writes at end of QK, V-frag reads 4 deep
# baseline (speedup 1.0000x reference)
; __device__ __forceinline__ void unit(LAS unsigned char* lds, int b, int h, int qb, const bf16_t* Q, const bf16_t* Kn, const bf16_t* Kr, const bf16_t* VT, const bf16_t* proj, bf16_t* ymix, int wv) {
;     ...
;     ATT_QK(0);
;     if (NT <= 4) ATT_SMA(0, true); else ATT_SMA(0, false);
;     pf[0][0] = pf2[0][0]; pf[0][1] = pf2[0][1]; pf[1][0] = pf2[1][0]; pf[1][1] = pf2[1][1];
;     float mref = mrun; f32x16 negm;
; #pragma unroll
;     for (int r = 0; r < 16; ++r) negm[r] = -mref;
;     int t = 0;
.LBB0_610:
	s_nop 4
	v_add_f32_e32 v2, 0, v38
	v_add_f32_e32 v2, v2, v39
	v_add_f32_e32 v2, v2, v36
	v_add_f32_e32 v2, v2, v37
	v_add_f32_e32 v2, v2, v34
	v_add_f32_e32 v2, v2, v35
	v_add_f32_e32 v2, v2, v40
	v_add_f32_e32 v2, v2, v41
	v_add_f32_e32 v2, v2, v46
	v_add_f32_e32 v2, v2, v47
	v_add_f32_e32 v2, v2, v44
	v_add_f32_e32 v2, v2, v45
	v_add_f32_e32 v2, v2, v42
	v_add_f32_e32 v2, v2, v43
	v_add_f32_e32 v2, v2, v48
	s_mov_b64 s[8:9], 0x400000
	v_add_f32_e32 v228, v2, v49
	v_lshlrev_b32_e32 v226, 3, v51
	v_lshl_add_u64 v[218:219], v[206:207], 0, s[8:9]
	v_fmac_f32_e32 v228, 0, v0
	v_xor_b32_e32 v95, 0x80000000, v217
	s_andn2_b64 vcc, exec, s[58:59]
	v_mul_u32_u24_e32 v227, 0x88, v50
	s_cbranch_vccnz .LBB0_619
	s_lshl_b32 s9, s55, 2
	v_mov_b32_e32 v14, v1
	v_mov_b32_e32 v15, v1
	s_lshl_b32 s8, s63, 2
	s_not_b32 s9, s9
	v_mov_b32_e32 v0, v1
	v_mov_b32_e32 v2, v1
	v_mov_b32_e32 v3, v1
	v_mov_b32_e32 v4, v1
	v_mov_b32_e32 v5, v1
	v_mov_b32_e32 v6, v1
	v_mov_b32_e32 v7, v1
	v_mov_b32_e32 v8, v1
	v_mov_b32_e32 v9, v1
	v_mov_b32_e32 v10, v1
	v_mov_b32_e32 v11, v1
	v_mov_b32_e32 v12, v1
	v_mov_b32_e32 v13, v1
	v_mov_b64_e32 v[78:79], v[14:15]
	v_mov_b64_e32 v[62:63], v[14:15]
	v_mov_b64_e32 v[46:47], v[14:15]
	v_mov_b64_e32 v[30:31], v[14:15]
	s_add_i32 s63, s9, s8
	s_movk_i32 s61, 0x4400
	s_mov_b32 s70, 0xc800
	s_movk_i32 s60, 0x6400
	s_mov_b32 s55, 0
	s_movk_i32 s58, 0xa0
	v_mov_b64_e32 v[76:77], v[12:13]
	v_mov_b64_e32 v[74:75], v[10:11]
	v_mov_b64_e32 v[72:73], v[8:9]
	v_mov_b64_e32 v[70:71], v[6:7]
	v_mov_b64_e32 v[68:69], v[4:5]
	v_mov_b64_e32 v[66:67], v[2:3]
	v_mov_b64_e32 v[64:65], v[0:1]
	v_mov_b64_e32 v[60:61], v[12:13]
	v_mov_b64_e32 v[58:59], v[10:11]
	v_mov_b64_e32 v[56:57], v[8:9]
	v_mov_b64_e32 v[54:55], v[6:7]
	v_mov_b64_e32 v[52:53], v[4:5]
	v_mov_b64_e32 v[50:51], v[2:3]
	v_mov_b64_e32 v[48:49], v[0:1]
	v_mov_b64_e32 v[44:45], v[12:13]
	v_mov_b64_e32 v[42:43], v[10:11]
	v_mov_b64_e32 v[40:41], v[8:9]
	v_mov_b64_e32 v[38:39], v[6:7]
	v_mov_b64_e32 v[36:37], v[4:5]
	v_mov_b64_e32 v[34:35], v[2:3]
	v_mov_b64_e32 v[32:33], v[0:1]
	v_mov_b64_e32 v[28:29], v[12:13]
	v_mov_b64_e32 v[26:27], v[10:11]
	v_mov_b64_e32 v[24:25], v[8:9]
	v_mov_b64_e32 v[22:23], v[6:7]
	v_mov_b64_e32 v[20:21], v[4:5]
	v_mov_b64_e32 v[18:19], v[2:3]
	v_mov_b64_e32 v[16:17], v[0:1]
	s_mov_b32 s8, 0
	s_mov_b32 s9, 0
	v_mov_b32_e32 v80, v95
	v_mov_b32_e32 v81, v95
	v_mov_b32_e32 v82, v95
	v_mov_b32_e32 v83, v95
	v_mov_b32_e32 v84, v95
	v_mov_b32_e32 v85, v95
	v_mov_b32_e32 v86, v95
	v_mov_b32_e32 v87, v95
	v_mov_b32_e32 v88, v95
	v_mov_b32_e32 v89, v95
	v_mov_b32_e32 v90, v95
	v_mov_b32_e32 v91, v95
	v_mov_b32_e32 v92, v95
	v_mov_b32_e32 v93, v95
	v_mov_b32_e32 v94, v95
	v_readlane_b32 s99, v254, 20
	s_nop 0
	s_cmp_lt_u32 s99, 0x80
	s_cbranch_scc1 .Lstg_in_a
	s_barrier
.Lstg_in_a:
.LBB0_612:
	s_sub_i32 s12, s58, 32
	s_lshl_b64 s[14:15], s[12:13], 11
	s_mov_b32 s59, s13
	v_lshl_add_u64 v[232:233], v[208:209], 0, s[14:15]
	s_lshl_b64 s[14:15], s[58:59], 11
	global_load_dwordx4 v[176:179], v[232:233], off
	v_lshl_add_u64 v[232:233], v[208:209], 0, s[14:15]
	s_lshl_b64 s[14:15], s[12:13], 7
	global_load_dwordx4 v[184:187], v[232:233], off
	v_lshl_add_u64 v[232:233], v[210:211], 0, s[14:15]
	global_load_dwordx4 v[188:191], v[232:233], off
	v_add_u32_e32 v0, s60, v215
	ds_read_b128 v[2:5], v0
	ds_read_b128 v[6:9], v0 offset:32
	v_mov_b64_e32 v[126:127], v[94:95]
	v_mov_b64_e32 v[124:125], v[92:93]
	v_mov_b64_e32 v[122:123], v[90:91]
	s_waitcnt lgkmcnt(1)
	v_mfma_f32_32x32x16_bf16 v[96:111], v[2:5], v[128:131], v[80:95]
	ds_read_b128 v[2:5], v0 offset:12800
	ds_read_b128 v[10:13], v0 offset:12832
	v_mov_b64_e32 v[120:121], v[88:89]
	v_mov_b64_e32 v[118:119], v[86:87]
	v_mov_b64_e32 v[116:117], v[84:85]
	v_mov_b64_e32 v[114:115], v[82:83]
	v_mov_b64_e32 v[112:113], v[80:81]
	s_waitcnt lgkmcnt(2)
	v_mfma_f32_32x32x16_bf16 v[96:111], v[6:9], v[132:135], v[96:111]
	s_mov_b32 s71, s9
	s_mov_b32 s72, s8
	s_waitcnt lgkmcnt(1)
	v_mfma_f32_32x32x16_bf16 v[112:127], v[2:5], v[128:131], v[112:127]
	ds_read_b128 v[2:5], v0 offset:64
	ds_read_b128 v[6:9], v0 offset:96
	s_waitcnt lgkmcnt(2)
	v_mfma_f32_32x32x16_bf16 v[112:127], v[10:13], v[132:135], v[112:127]
	s_waitcnt lgkmcnt(1)
	v_mfma_f32_32x32x16_bf16 v[96:111], v[2:5], v[136:139], v[96:111]
	ds_read_b128 v[2:5], v0 offset:12864
	ds_read_b128 v[10:13], v0 offset:12896
	s_waitcnt lgkmcnt(1)
	v_mfma_f32_32x32x16_bf16 v[112:127], v[2:5], v[136:139], v[112:127]
	v_mfma_f32_32x32x16_bf16 v[96:111], v[6:9], v[140:143], v[96:111]
	ds_read_b128 v[2:5], v0 offset:128
	ds_read_b128 v[6:9], v0 offset:160
	s_waitcnt lgkmcnt(2)
	v_mfma_f32_32x32x16_bf16 v[112:127], v[10:13], v[140:143], v[112:127]
	s_waitcnt lgkmcnt(1)
	v_mfma_f32_32x32x16_bf16 v[96:111], v[2:5], v[144:147], v[96:111]
	ds_read_b128 v[2:5], v0 offset:12928
	ds_read_b128 v[10:13], v0 offset:12960
	s_waitcnt lgkmcnt(1)
	v_mfma_f32_32x32x16_bf16 v[112:127], v[2:5], v[144:147], v[112:127]
	v_mfma_f32_32x32x16_bf16 v[96:111], v[6:9], v[148:151], v[96:111]
	ds_read_b128 v[2:5], v0 offset:192
	ds_read_b128 v[6:9], v0 offset:224
	s_waitcnt lgkmcnt(2)
	v_mfma_f32_32x32x16_bf16 v[112:127], v[10:13], v[148:151], v[112:127]
	s_waitcnt lgkmcnt(1)
	v_mfma_f32_32x32x16_bf16 v[96:111], v[2:5], v[152:155], v[96:111]
	ds_read_b128 v[2:5], v0 offset:12992
	ds_read_b128 v[10:13], v0 offset:13024
	s_waitcnt lgkmcnt(1)
	v_mfma_f32_32x32x16_bf16 v[112:127], v[2:5], v[152:155], v[112:127]
	v_mfma_f32_32x32x16_bf16 v[96:111], v[6:9], v[156:159], v[96:111]
	ds_read_b128 v[2:5], v0 offset:256
	ds_read_b128 v[6:9], v0 offset:288
	s_waitcnt lgkmcnt(2)
; __device__ __forceinline__ void unit(LAS unsigned char* lds, int b, int h, int qb, const bf16_t* Q, const bf16_t* Kn, const bf16_t* Kr, const bf16_t* VT, const bf16_t* proj, bf16_t* ymix, int wv) {
;     ...
;     f32x16 o[4];
; #pragma unroll
;     for (int i = 0; i < 4; ++i) o[i] = (f32x16){0, 0, 0, 0, 0, 0, 0, 0, 0, 0, 0, 0, 0, 0, 0, 0};
;     float mrun = -INFINITY, lrun = 0.f;
;     const int qidx = q0 + 32 * wave + l32;
;     f32x16 p0, p1; bf16x8 pf[2][2];
	v_mfma_f32_32x32x16_bf16 v[112:127], v[10:13], v[156:159], v[112:127]
	s_waitcnt lgkmcnt(1)
	v_mfma_f32_32x32x16_bf16 v[96:111], v[2:5], v[160:163], v[96:111]
	ds_read_b128 v[2:5], v0 offset:13056
	ds_read_b128 v[10:13], v0 offset:13088
	s_waitcnt lgkmcnt(1)
	v_mfma_f32_32x32x16_bf16 v[112:127], v[2:5], v[160:163], v[112:127]
	ds_read_b128 v[2:5], v0 offset:320
	v_mfma_f32_32x32x16_bf16 v[96:111], v[6:9], v[164:167], v[96:111]
	s_waitcnt lgkmcnt(1)
	v_mfma_f32_32x32x16_bf16 v[112:127], v[10:13], v[164:167], v[112:127]
	ds_read_b128 v[6:9], v0 offset:13120
	ds_read_b128 v[10:13], v0 offset:352
	s_waitcnt lgkmcnt(2)
	v_mfma_f32_32x32x16_bf16 v[96:111], v[2:5], v[168:171], v[96:111]
	s_add_i32 s12, s58, 0xffffffa0
	ds_read_b128 v[230:233], v0 offset:13152
	s_waitcnt lgkmcnt(2)
	v_mfma_f32_32x32x16_bf16 v[112:127], v[6:9], v[168:171], v[112:127]
	s_lshl_b64 s[14:15], s[12:13], 1
	v_lshl_add_u64 v[8:9], v[218:219], 0, s[14:15]
	v_lshl_add_u64 v[2:3], v[206:207], 0, s[14:15]
	global_load_dwordx4 v[2:5], v[2:3], off
	s_nop 0
	s_nop 0
	global_load_dwordx4 v[6:9], v[8:9], off
	s_waitcnt lgkmcnt(1)
	v_mfma_f32_32x32x16_bf16 v[96:111], v[10:13], v[172:175], v[96:111]
	s_waitcnt lgkmcnt(0)
	v_mfma_f32_32x32x16_bf16 v[112:127], v[230:233], v[172:175], v[112:127]
	v_add_u32_e32 v253, s70, v212
	s_waitcnt vmcnt(4)
	ds_write_b128 v253, v[176:179]
	s_waitcnt vmcnt(3)
	ds_write_b128 v253, v[184:187] offset:12800
	v_add_u32_e32 v253, s70, v214
	s_waitcnt vmcnt(2)
	ds_write_b128 v253, v[188:191] offset:256
	s_waitcnt lgkmcnt(0)
	s_barrier
	s_add_i32 s8, s9, 0
	s_add_i32 s8, s8, 0x12c00
	v_add_u32_e32 v0, s8, v227
	v_add_u32_e32 v231, v0, v226
	v_add_u32_e32 v229, 0x1000, v231
	v_add_u32_e32 v230, 0x2000, v231
	v_add_u32_e32 v252, 0x3000, v231
	ds_read2_b64 v[234:237], v231 offset1:2
	ds_read2_b64 v[238:241], v229 offset0:32 offset1:34
	ds_read2_b64 v[244:247], v230 offset0:64 offset1:66
	ds_read2_b64 v[248:251], v252 offset0:96 offset1:98
	s_nop 2
	v_max_f32_e32 v0, v96, v96
	v_max_f32_e32 v0, 0xff800000, v0
	v_max3_f32 v0, v0, v97, v98
	s_waitcnt lgkmcnt(3)
	v_mfma_f32_32x32x16_bf16 v[64:79], v[234:237], v[200:203], v[64:79]
	ds_read2_b64 v[234:237], v231 offset0:4 offset1:6
	v_max3_f32 v10, v112, s64, v113
	v_max3_f32 v14, v10, v114, v115
	s_waitcnt lgkmcnt(3)
	v_mfma_f32_32x32x16_bf16 v[48:63], v[238:241], v[200:203], v[48:63]
	ds_read2_b64 v[238:241], v229 offset0:36 offset1:38
	v_max3_f32 v0, v0, v99, v100
	v_max3_f32 v14, v14, v116, v117
	v_max3_f32 v0, v0, v101, v102
	v_max3_f32 v14, v14, v118, v119
	s_waitcnt lgkmcnt(3)
	v_mfma_f32_32x32x16_bf16 v[32:47], v[244:247], v[200:203], v[32:47]
	ds_read2_b64 v[244:247], v230 offset0:68 offset1:70
	v_max3_f32 v0, v0, v103, v104
	v_max3_f32 v14, v14, v120, v121
	v_max3_f32 v0, v0, v105, v106
	v_max3_f32 v14, v14, v122, v123
	s_waitcnt lgkmcnt(3)
	v_mfma_f32_32x32x16_bf16 v[16:31], v[248:251], v[200:203], v[16:31]
	ds_read2_b64 v[248:251], v252 offset0:100 offset1:102
	v_max3_f32 v0, v0, v107, v108
	v_max3_f32 v10, v14, v124, v125
	v_max3_f32 v0, v0, v109, v110
	v_max3_f32 v14, v10, v126, v127
	v_max3_f32 v0, v0, v111, v14
	v_mov_b32_e32 v14, v222
	s_waitcnt lgkmcnt(3)
	v_mfma_f32_32x32x16_bf16 v[64:79], v[234:237], v[196:199], v[64:79]
	ds_read2_b64 v[234:237], v231 offset0:8 offset1:10
	v_lshlrev_b32_e32 v14, 2, v14
	v_xor_b32_e32 v14, 0x80, v14
	ds_bpermute_b32 v14, v14, v0
	s_waitcnt lgkmcnt(0)
	v_max_f32_e32 v14, v14, v14
	v_max_f32_e32 v0, v0, v14
	v_cmp_lt_f32_e32 vcc, s65, v0
	s_cbranch_vccz .LBB0_614
	v_max_f32_e32 v0, v0, v0
	v_max_f32_e32 v0, 0, v0
	v_add_f32_e32 v217, v217, v0
	v_pk_add_f32 v[96:97], v[96:97], v[0:1] op_sel_hi:[1,0] neg_lo:[0,1] neg_hi:[0,1]
	v_pk_add_f32 v[112:113], v[112:113], v[0:1] op_sel_hi:[1,0] neg_lo:[0,1] neg_hi:[0,1]
	v_pk_add_f32 v[98:99], v[98:99], v[0:1] op_sel_hi:[1,0] neg_lo:[0,1] neg_hi:[0,1]
	v_pk_add_f32 v[114:115], v[114:115], v[0:1] op_sel_hi:[1,0] neg_lo:[0,1] neg_hi:[0,1]
	v_pk_add_f32 v[100:101], v[100:101], v[0:1] op_sel_hi:[1,0] neg_lo:[0,1] neg_hi:[0,1]
	v_pk_add_f32 v[116:117], v[116:117], v[0:1] op_sel_hi:[1,0] neg_lo:[0,1] neg_hi:[0,1]
	v_pk_add_f32 v[102:103], v[102:103], v[0:1] op_sel_hi:[1,0] neg_lo:[0,1] neg_hi:[0,1]
	v_pk_add_f32 v[118:119], v[118:119], v[0:1] op_sel_hi:[1,0] neg_lo:[0,1] neg_hi:[0,1]
	v_pk_add_f32 v[104:105], v[104:105], v[0:1] op_sel_hi:[1,0] neg_lo:[0,1] neg_hi:[0,1]
	v_pk_add_f32 v[120:121], v[120:121], v[0:1] op_sel_hi:[1,0] neg_lo:[0,1] neg_hi:[0,1]
	v_pk_add_f32 v[106:107], v[106:107], v[0:1] op_sel_hi:[1,0] neg_lo:[0,1] neg_hi:[0,1]
	v_pk_add_f32 v[122:123], v[122:123], v[0:1] op_sel_hi:[1,0] neg_lo:[0,1] neg_hi:[0,1]
	v_pk_add_f32 v[108:109], v[108:109], v[0:1] op_sel_hi:[1,0] neg_lo:[0,1] neg_hi:[0,1]
	v_pk_add_f32 v[124:125], v[124:125], v[0:1] op_sel_hi:[1,0] neg_lo:[0,1] neg_hi:[0,1]
	v_pk_add_f32 v[110:111], v[110:111], v[0:1] op_sel_hi:[1,0] neg_lo:[0,1] neg_hi:[0,1]
	v_pk_add_f32 v[126:127], v[126:127], v[0:1] op_sel_hi:[1,0] neg_lo:[0,1] neg_hi:[0,1]
	v_exp_f32_e64 v0, -v0
	v_xor_b32_e32 v80, 0x80000000, v217
	v_mov_b32_e32 v81, v80
	v_mov_b32_e32 v82, v80
	v_mov_b32_e32 v83, v80
	v_mov_b32_e32 v84, v80
	v_mov_b32_e32 v85, v80
	v_mov_b32_e32 v86, v80
	v_mov_b32_e32 v87, v80
	v_mov_b32_e32 v88, v80
	v_mov_b32_e32 v89, v80
	v_mov_b32_e32 v90, v80
	v_mov_b32_e32 v91, v80
	v_mov_b32_e32 v92, v80
	v_mov_b32_e32 v93, v80
	v_mov_b32_e32 v94, v80
	v_mov_b32_e32 v95, v80
	s_branch .LBB0_615

.LBB0_615:
	v_mfma_f32_32x32x16_bf16 v[48:63], v[238:241], v[196:199], v[48:63]
	ds_read2_b64 v[238:241], v229 offset0:40 offset1:42
	v_exp_f32_e32 v220, v96
	v_exp_f32_e32 v221, v112
	v_exp_f32_e32 v14, v97
	v_exp_f32_e32 v15, v113
	v_mfma_f32_32x32x16_bf16 v[32:47], v[244:247], v[196:199], v[32:47]
	ds_read2_b64 v[244:247], v230 offset0:72 offset1:74
	v_exp_f32_e32 v12, v98
	v_exp_f32_e32 v13, v114
	v_exp_f32_e32 v10, v99
	v_exp_f32_e32 v11, v115
	v_mfma_f32_32x32x16_bf16 v[16:31], v[248:251], v[196:199], v[16:31]
	ds_read2_b64 v[248:251], v252 offset0:104 offset1:106
	v_exp_f32_e32 v98, v100
	v_exp_f32_e32 v99, v116
	v_exp_f32_e32 v96, v101
	v_exp_f32_e32 v97, v117
	v_mfma_f32_32x32x16_bf16 v[64:79], v[234:237], v[192:195], v[64:79]
	ds_read2_b64 v[234:237], v231 offset0:12 offset1:14
	v_exp_f32_e32 v112, v102
	v_exp_f32_e32 v113, v118
	v_exp_f32_e32 v100, v103
	v_exp_f32_e32 v101, v119
	s_waitcnt lgkmcnt(3)
	v_mfma_f32_32x32x16_bf16 v[48:63], v[238:241], v[192:195], v[48:63]
	ds_read2_b64 v[238:241], v229 offset0:44 offset1:46
	v_exp_f32_e32 v114, v104
	v_exp_f32_e32 v115, v120
	v_exp_f32_e32 v102, v105
	v_exp_f32_e32 v103, v121
	s_waitcnt lgkmcnt(3)
	v_mfma_f32_32x32x16_bf16 v[32:47], v[244:247], v[192:195], v[32:47]
	ds_read2_b64 v[244:247], v230 offset0:76 offset1:78
	v_exp_f32_e32 v116, v106
	v_exp_f32_e32 v117, v122
	v_exp_f32_e32 v104, v107
	v_exp_f32_e32 v105, v123
	s_waitcnt lgkmcnt(3)
	v_mfma_f32_32x32x16_bf16 v[16:31], v[248:251], v[192:195], v[16:31]
	ds_read2_b64 v[248:251], v252 offset0:108 offset1:110
	v_exp_f32_e32 v118, v108
	v_exp_f32_e32 v119, v124
	v_exp_f32_e32 v106, v109
	v_exp_f32_e32 v107, v125
	s_waitcnt lgkmcnt(3)
	v_mfma_f32_32x32x16_bf16 v[64:79], v[234:237], v[180:183], v[64:79]
	v_exp_f32_e32 v120, v110
	v_exp_f32_e32 v121, v126
	v_exp_f32_e32 v108, v111
	v_exp_f32_e32 v109, v127
	s_waitcnt lgkmcnt(2)
	v_mfma_f32_32x32x16_bf16 v[48:63], v[238:241], v[180:183], v[48:63]
	v_cvt_pk_bf16_f32 v200, v220, v14
	v_cvt_pk_bf16_f32 v201, v12, v10
	v_cvt_pk_bf16_f32 v202, v98, v96
	v_cvt_pk_bf16_f32 v203, v112, v100
	v_cvt_pk_bf16_f32 v196, v114, v102
	v_cvt_pk_bf16_f32 v197, v116, v104
	v_cvt_pk_bf16_f32 v198, v118, v106
	v_cvt_pk_bf16_f32 v199, v120, v108
	s_waitcnt lgkmcnt(1)
	v_mfma_f32_32x32x16_bf16 v[32:47], v[244:247], v[180:183], v[32:47]
	v_cvt_pk_bf16_f32 v192, v221, v15
	v_cvt_pk_bf16_f32 v193, v13, v11
	v_cvt_pk_bf16_f32 v194, v99, v97
	v_cvt_pk_bf16_f32 v195, v113, v101
	s_waitcnt lgkmcnt(0)
	v_mfma_f32_32x32x16_bf16 v[16:31], v[248:251], v[180:183], v[16:31]
	v_cvt_pk_bf16_f32 v180, v115, v103
	v_cvt_pk_bf16_f32 v181, v117, v105
	v_cvt_pk_bf16_f32 v182, v119, v107
	v_cvt_pk_bf16_f32 v183, v121, v109
	v_cmp_gt_f32_e32 vcc, 1.0, v0
	s_cbranch_vccz .LBB0_617
	v_pk_mul_f32 v[78:79], v[0:1], v[78:79] op_sel_hi:[0,1]
	v_pk_mul_f32 v[76:77], v[0:1], v[76:77] op_sel_hi:[0,1]
	v_pk_mul_f32 v[74:75], v[0:1], v[74:75] op_sel_hi:[0,1]
	v_pk_mul_f32 v[72:73], v[0:1], v[72:73] op_sel_hi:[0,1]
	v_pk_mul_f32 v[70:71], v[0:1], v[70:71] op_sel_hi:[0,1]
	v_pk_mul_f32 v[68:69], v[0:1], v[68:69] op_sel_hi:[0,1]
	v_pk_mul_f32 v[66:67], v[0:1], v[66:67] op_sel_hi:[0,1]
	v_pk_mul_f32 v[64:65], v[0:1], v[64:65] op_sel_hi:[0,1]
	v_pk_mul_f32 v[62:63], v[0:1], v[62:63] op_sel_hi:[0,1]
	v_pk_mul_f32 v[60:61], v[0:1], v[60:61] op_sel_hi:[0,1]
	v_pk_mul_f32 v[58:59], v[0:1], v[58:59] op_sel_hi:[0,1]
	v_pk_mul_f32 v[56:57], v[0:1], v[56:57] op_sel_hi:[0,1]
	v_pk_mul_f32 v[54:55], v[0:1], v[54:55] op_sel_hi:[0,1]
	v_pk_mul_f32 v[52:53], v[0:1], v[52:53] op_sel_hi:[0,1]
	v_pk_mul_f32 v[50:51], v[0:1], v[50:51] op_sel_hi:[0,1]
	v_pk_mul_f32 v[48:49], v[0:1], v[48:49] op_sel_hi:[0,1]
	v_pk_mul_f32 v[46:47], v[0:1], v[46:47] op_sel_hi:[0,1]
	v_pk_mul_f32 v[44:45], v[0:1], v[44:45] op_sel_hi:[0,1]
	v_pk_mul_f32 v[42:43], v[0:1], v[42:43] op_sel_hi:[0,1]
	v_pk_mul_f32 v[40:41], v[0:1], v[40:41] op_sel_hi:[0,1]
	v_pk_mul_f32 v[38:39], v[0:1], v[38:39] op_sel_hi:[0,1]
	v_pk_mul_f32 v[36:37], v[0:1], v[36:37] op_sel_hi:[0,1]
	v_pk_mul_f32 v[34:35], v[0:1], v[34:35] op_sel_hi:[0,1]
	v_pk_mul_f32 v[32:33], v[0:1], v[32:33] op_sel_hi:[0,1]
	v_pk_mul_f32 v[30:31], v[0:1], v[30:31] op_sel_hi:[0,1]
	v_pk_mul_f32 v[28:29], v[0:1], v[28:29] op_sel_hi:[0,1]
	v_pk_mul_f32 v[26:27], v[0:1], v[26:27] op_sel_hi:[0,1]
	v_pk_mul_f32 v[24:25], v[0:1], v[24:25] op_sel_hi:[0,1]
	v_pk_mul_f32 v[22:23], v[0:1], v[22:23] op_sel_hi:[0,1]
	v_pk_mul_f32 v[20:21], v[0:1], v[20:21] op_sel_hi:[0,1]
	v_pk_mul_f32 v[18:19], v[0:1], v[18:19] op_sel_hi:[0,1]
	v_pk_mul_f32 v[16:17], v[0:1], v[16:17] op_sel_hi:[0,1]

; #define ATT_TOP(t) do { if ((t) + 2 < NT) ATT_LOADK((t) + 2); if ((t) + 1 < NT) ATT_LOADV((t) + 1); } while (0)
; #define ATT_BOT(t) do { if ((t) + 2 < NT) ATT_STOREK(k2); if ((t) + 1 < NT) ATT_STOREV(v1); __syncthreads(); \
;         { const int kk = k0; k0 = k1; k1 = k2; k2 = kk; const int vv = v0; v0 = v1; v1 = vv; } } while (0)
; #define ATT_RESC() do { if (__any(alpha_n < 1.f)) { _Pragma("unroll") for (int i = 0; i < 4; ++i) _Pragma("unroll") for (int r = 0; r < 16; ++r) o[i][r] *= alpha_n; } } while (0)
; __device__ __forceinline__ void unit(LAS unsigned char* lds, int b, int h, int qb, const bf16_t* Q, const bf16_t* Kn, const bf16_t* Kr, const bf16_t* VT, const bf16_t* proj, bf16_t* ymix, int wv) {
;     ...
;     for (; t + 1 < NT - 4; ++t) { ATT_TOP(t); ATT_QKN(k1); __builtin_amdgcn_sched_barrier(0); ATT_FUSED(t + 1, false); ATT_RESC(); ATT_BOT(t); }
;     for (; t + 1 < NT; ++t) { ATT_TOP(t); ATT_QKN(k1); __builtin_amdgcn_sched_barrier(0); ATT_FUSED(t + 1, true); ATT_RESC(); ATT_BOT(t); }
;     ...
;     { ATT_PV(v0); ATT_BOT(t); }
.Lstg_exit_a:
	s_cmp_lt_u32 s99, 0x80
	s_cbranch_scc0 .LBB0_620
	s_barrier
	s_branch .LBB0_620

; __device__ __forceinline__ void unit(LAS unsigned char* lds, int b, int h, int qb, const bf16_t* Q, const bf16_t* Kn, const bf16_t* Kr, const bf16_t* VT, const bf16_t* proj, bf16_t* ymix, int wv) {
;     ...
;     ATT_QK(0);
;     if (NT <= 4) ATT_SMA(0, true); else ATT_SMA(0, false);
;     pf[0][0] = pf2[0][0]; pf[0][1] = pf2[0][1]; pf[1][0] = pf2[1][0]; pf[1][1] = pf2[1][1];
;     float mref = mrun; f32x16 negm;
; #pragma unroll
;     for (int r = 0; r < 16; ++r) negm[r] = -mref;
;     int t = 0;
.LBB0_1175:
	s_nop 4
	v_add_f32_e32 v2, 0, v38
	v_add_f32_e32 v2, v2, v39
	v_add_f32_e32 v2, v2, v36
	v_add_f32_e32 v2, v2, v37
	v_add_f32_e32 v2, v2, v34
	v_add_f32_e32 v2, v2, v35
	v_add_f32_e32 v2, v2, v40
	v_add_f32_e32 v2, v2, v41
	v_add_f32_e32 v2, v2, v46
	v_add_f32_e32 v2, v2, v47
	v_add_f32_e32 v2, v2, v44
	v_add_f32_e32 v2, v2, v45
	v_add_f32_e32 v2, v2, v42
	v_add_f32_e32 v2, v2, v43
	v_add_f32_e32 v2, v2, v48
	v_add_f32_e32 v228, v2, v49
	v_lshlrev_b32_e32 v226, 3, v51
	v_lshl_add_u64 v[218:219], v[206:207], 0, s[8:9]
	v_fmac_f32_e32 v228, 0, v0
	v_xor_b32_e32 v95, 0x80000000, v217
	s_andn2_b64 vcc, exec, s[36:37]
	v_mul_u32_u24_e32 v227, 0x88, v50
	s_cbranch_vccnz .LBB0_1184
	s_lshl_b32 s17, s17, 2
	v_mov_b32_e32 v14, v1
	v_mov_b32_e32 v15, v1
	s_lshl_b32 s6, s41, 2
	s_not_b32 s17, s17
	v_mov_b32_e32 v0, v1
	v_mov_b32_e32 v2, v1
	v_mov_b32_e32 v3, v1
	v_mov_b32_e32 v4, v1
	v_mov_b32_e32 v5, v1
	v_mov_b32_e32 v6, v1
	v_mov_b32_e32 v7, v1
	v_mov_b32_e32 v8, v1
	v_mov_b32_e32 v9, v1
	v_mov_b32_e32 v10, v1
	v_mov_b32_e32 v11, v1
	v_mov_b32_e32 v12, v1
	v_mov_b32_e32 v13, v1
	v_mov_b64_e32 v[78:79], v[14:15]
	v_mov_b64_e32 v[62:63], v[14:15]
	v_mov_b64_e32 v[46:47], v[14:15]
	v_mov_b64_e32 v[30:31], v[14:15]
	s_add_i32 s41, s17, s6
	s_movk_i32 s39, 0x4400
	s_mov_b32 s57, 0xc800
	s_movk_i32 s38, 0x6400
	s_mov_b32 s17, 0
	s_movk_i32 s36, 0xa0
	v_mov_b64_e32 v[76:77], v[12:13]
	v_mov_b64_e32 v[74:75], v[10:11]
	v_mov_b64_e32 v[72:73], v[8:9]
	v_mov_b64_e32 v[70:71], v[6:7]
	v_mov_b64_e32 v[68:69], v[4:5]
	v_mov_b64_e32 v[66:67], v[2:3]
	v_mov_b64_e32 v[64:65], v[0:1]
	v_mov_b64_e32 v[60:61], v[12:13]
	v_mov_b64_e32 v[58:59], v[10:11]
	v_mov_b64_e32 v[56:57], v[8:9]
	v_mov_b64_e32 v[54:55], v[6:7]
	v_mov_b64_e32 v[52:53], v[4:5]
	v_mov_b64_e32 v[50:51], v[2:3]
	v_mov_b64_e32 v[48:49], v[0:1]
	v_mov_b64_e32 v[44:45], v[12:13]
	v_mov_b64_e32 v[42:43], v[10:11]
	v_mov_b64_e32 v[40:41], v[8:9]
	v_mov_b64_e32 v[38:39], v[6:7]
	v_mov_b64_e32 v[36:37], v[4:5]
	v_mov_b64_e32 v[34:35], v[2:3]
	v_mov_b64_e32 v[32:33], v[0:1]
	v_mov_b64_e32 v[28:29], v[12:13]
	v_mov_b64_e32 v[26:27], v[10:11]
	v_mov_b64_e32 v[24:25], v[8:9]
	v_mov_b64_e32 v[22:23], v[6:7]
	v_mov_b64_e32 v[20:21], v[4:5]
	v_mov_b64_e32 v[18:19], v[2:3]
	v_mov_b64_e32 v[16:17], v[0:1]
	s_mov_b32 s60, 0
	s_mov_b32 s59, 0
	v_mov_b32_e32 v80, v95
	v_mov_b32_e32 v81, v95
	v_mov_b32_e32 v82, v95
	v_mov_b32_e32 v83, v95
	v_mov_b32_e32 v84, v95
	v_mov_b32_e32 v85, v95
	v_mov_b32_e32 v86, v95
	v_mov_b32_e32 v87, v95
	v_mov_b32_e32 v88, v95
	v_mov_b32_e32 v89, v95
	v_mov_b32_e32 v90, v95
	v_mov_b32_e32 v91, v95
	v_mov_b32_e32 v92, v95
	v_mov_b32_e32 v93, v95
	v_mov_b32_e32 v94, v95
	v_readlane_b32 s99, v254, 20
	s_nop 0
	s_cmp_lt_u32 s99, 0x80
	s_cbranch_scc1 .Lstg_in_b
	s_barrier
.Lstg_in_b:
.LBB0_1177:
	s_sub_i32 s6, s36, 32
	s_lshl_b64 s[62:63], s[6:7], 11
	s_mov_b32 s37, s7
	v_lshl_add_u64 v[232:233], v[208:209], 0, s[62:63]
	s_lshl_b64 s[62:63], s[36:37], 11
	global_load_dwordx4 v[176:179], v[232:233], off
	v_lshl_add_u64 v[232:233], v[208:209], 0, s[62:63]
	s_lshl_b64 s[62:63], s[6:7], 7
	global_load_dwordx4 v[180:183], v[232:233], off
	v_lshl_add_u64 v[232:233], v[210:211], 0, s[62:63]
	global_load_dwordx4 v[184:187], v[232:233], off
	v_add_u32_e32 v0, s38, v215
	ds_read_b128 v[2:5], v0
	ds_read_b128 v[6:9], v0 offset:32
	v_mov_b64_e32 v[126:127], v[94:95]
	v_mov_b64_e32 v[124:125], v[92:93]
	v_mov_b64_e32 v[122:123], v[90:91]
	s_waitcnt lgkmcnt(1)
	v_mfma_f32_32x32x16_bf16 v[96:111], v[2:5], v[128:131], v[80:95]
	ds_read_b128 v[2:5], v0 offset:12800
	ds_read_b128 v[10:13], v0 offset:12832
	v_mov_b64_e32 v[120:121], v[88:89]
	v_mov_b64_e32 v[118:119], v[86:87]
	v_mov_b64_e32 v[116:117], v[84:85]
	v_mov_b64_e32 v[114:115], v[82:83]
	v_mov_b64_e32 v[112:113], v[80:81]
	s_waitcnt lgkmcnt(2)
	v_mfma_f32_32x32x16_bf16 v[96:111], v[6:9], v[132:135], v[96:111]
	s_mov_b32 s58, s59
	s_mov_b32 s59, s60
	s_waitcnt lgkmcnt(1)
	v_mfma_f32_32x32x16_bf16 v[112:127], v[2:5], v[128:131], v[112:127]
	ds_read_b128 v[2:5], v0 offset:64
	ds_read_b128 v[6:9], v0 offset:96
	s_waitcnt lgkmcnt(2)
	v_mfma_f32_32x32x16_bf16 v[112:127], v[10:13], v[132:135], v[112:127]
	s_waitcnt lgkmcnt(1)
	v_mfma_f32_32x32x16_bf16 v[96:111], v[2:5], v[136:139], v[96:111]
	ds_read_b128 v[2:5], v0 offset:12864
	ds_read_b128 v[10:13], v0 offset:12896
	s_waitcnt lgkmcnt(1)
	v_mfma_f32_32x32x16_bf16 v[112:127], v[2:5], v[136:139], v[112:127]
	v_mfma_f32_32x32x16_bf16 v[96:111], v[6:9], v[140:143], v[96:111]
	ds_read_b128 v[2:5], v0 offset:128
	ds_read_b128 v[6:9], v0 offset:160
	s_waitcnt lgkmcnt(2)
	v_mfma_f32_32x32x16_bf16 v[112:127], v[10:13], v[140:143], v[112:127]
	s_waitcnt lgkmcnt(1)
	v_mfma_f32_32x32x16_bf16 v[96:111], v[2:5], v[144:147], v[96:111]
	ds_read_b128 v[2:5], v0 offset:12928
	ds_read_b128 v[10:13], v0 offset:12960
	s_waitcnt lgkmcnt(1)
	v_mfma_f32_32x32x16_bf16 v[112:127], v[2:5], v[144:147], v[112:127]
	v_mfma_f32_32x32x16_bf16 v[96:111], v[6:9], v[148:151], v[96:111]
	ds_read_b128 v[2:5], v0 offset:192
	ds_read_b128 v[6:9], v0 offset:224
	s_waitcnt lgkmcnt(2)
	v_mfma_f32_32x32x16_bf16 v[112:127], v[10:13], v[148:151], v[112:127]
	s_waitcnt lgkmcnt(1)
	v_mfma_f32_32x32x16_bf16 v[96:111], v[2:5], v[152:155], v[96:111]
	ds_read_b128 v[2:5], v0 offset:12992
	ds_read_b128 v[10:13], v0 offset:13024
	s_waitcnt lgkmcnt(1)
	v_mfma_f32_32x32x16_bf16 v[112:127], v[2:5], v[152:155], v[112:127]
	v_mfma_f32_32x32x16_bf16 v[96:111], v[6:9], v[156:159], v[96:111]
	ds_read_b128 v[2:5], v0 offset:256
	ds_read_b128 v[6:9], v0 offset:288
	s_waitcnt lgkmcnt(2)
; __device__ __forceinline__ void unit(LAS unsigned char* lds, int b, int h, int qb, const bf16_t* Q, const bf16_t* Kn, const bf16_t* Kr, const bf16_t* VT, const bf16_t* proj, bf16_t* ymix, int wv) {
;     ...
;     f32x16 o[4];
; #pragma unroll
;     for (int i = 0; i < 4; ++i) o[i] = (f32x16){0, 0, 0, 0, 0, 0, 0, 0, 0, 0, 0, 0, 0, 0, 0, 0};
;     float mrun = -INFINITY, lrun = 0.f;
;     const int qidx = q0 + 32 * wave + l32;
;     f32x16 p0, p1; bf16x8 pf[2][2];
	v_mfma_f32_32x32x16_bf16 v[112:127], v[10:13], v[156:159], v[112:127]
	s_waitcnt lgkmcnt(1)
	v_mfma_f32_32x32x16_bf16 v[96:111], v[2:5], v[160:163], v[96:111]
	ds_read_b128 v[2:5], v0 offset:13056
	ds_read_b128 v[10:13], v0 offset:13088
	s_waitcnt lgkmcnt(1)
	v_mfma_f32_32x32x16_bf16 v[112:127], v[2:5], v[160:163], v[112:127]
	ds_read_b128 v[2:5], v0 offset:320
	v_mfma_f32_32x32x16_bf16 v[96:111], v[6:9], v[164:167], v[96:111]
	s_waitcnt lgkmcnt(1)
	v_mfma_f32_32x32x16_bf16 v[112:127], v[10:13], v[164:167], v[112:127]
	ds_read_b128 v[6:9], v0 offset:13120
	ds_read_b128 v[10:13], v0 offset:352
	s_waitcnt lgkmcnt(2)
	v_mfma_f32_32x32x16_bf16 v[96:111], v[2:5], v[168:171], v[96:111]
	s_add_i32 s6, s36, 0xffffffa0
	ds_read_b128 v[230:233], v0 offset:13152
	s_waitcnt lgkmcnt(2)
	v_mfma_f32_32x32x16_bf16 v[112:127], v[6:9], v[168:171], v[112:127]
	s_lshl_b64 s[62:63], s[6:7], 1
	v_lshl_add_u64 v[8:9], v[218:219], 0, s[62:63]
	v_lshl_add_u64 v[2:3], v[206:207], 0, s[62:63]
	global_load_dwordx4 v[2:5], v[2:3], off
	s_nop 0
	s_nop 0
	global_load_dwordx4 v[6:9], v[8:9], off
	s_waitcnt lgkmcnt(1)
	v_mfma_f32_32x32x16_bf16 v[96:111], v[10:13], v[172:175], v[96:111]
	s_waitcnt lgkmcnt(0)
	v_mfma_f32_32x32x16_bf16 v[112:127], v[230:233], v[172:175], v[112:127]
	v_add_u32_e32 v253, s57, v212
	s_waitcnt vmcnt(4)
	ds_write_b128 v253, v[176:179]
	s_waitcnt vmcnt(3)
	ds_write_b128 v253, v[180:183] offset:12800
	v_add_u32_e32 v253, s57, v214
	s_waitcnt vmcnt(2)
	ds_write_b128 v253, v[184:187] offset:256
	s_waitcnt lgkmcnt(0)
	s_barrier
	s_add_i32 s6, s58, 0
	s_add_i32 s6, s6, 0x12c00
	v_add_u32_e32 v0, s6, v227
	v_add_u32_e32 v231, v0, v226
	v_add_u32_e32 v229, 0x1000, v231
	v_add_u32_e32 v230, 0x2000, v231
	v_add_u32_e32 v252, 0x3000, v231
	ds_read2_b64 v[234:237], v231 offset1:2
	ds_read2_b64 v[238:241], v229 offset0:32 offset1:34
	ds_read2_b64 v[244:247], v230 offset0:64 offset1:66
	ds_read2_b64 v[248:251], v252 offset0:96 offset1:98
	s_nop 2
	v_max_f32_e32 v0, v96, v96
	v_max_f32_e32 v0, 0xff800000, v0
	v_max3_f32 v0, v0, v97, v98
	s_waitcnt lgkmcnt(3)
	v_mfma_f32_32x32x16_bf16 v[64:79], v[234:237], v[200:203], v[64:79]
	ds_read2_b64 v[234:237], v231 offset0:4 offset1:6
	v_max3_f32 v10, v112, s52, v113
	v_max3_f32 v14, v10, v114, v115
	s_waitcnt lgkmcnt(3)
	v_mfma_f32_32x32x16_bf16 v[48:63], v[238:241], v[200:203], v[48:63]
	ds_read2_b64 v[238:241], v229 offset0:36 offset1:38
	v_max3_f32 v0, v0, v99, v100
	v_max3_f32 v14, v14, v116, v117
	v_max3_f32 v0, v0, v101, v102
	v_max3_f32 v14, v14, v118, v119
	s_waitcnt lgkmcnt(3)
	v_mfma_f32_32x32x16_bf16 v[32:47], v[244:247], v[200:203], v[32:47]
	ds_read2_b64 v[244:247], v230 offset0:68 offset1:70
	v_max3_f32 v0, v0, v103, v104
	v_max3_f32 v14, v14, v120, v121
	v_max3_f32 v0, v0, v105, v106
	v_max3_f32 v14, v14, v122, v123
	s_waitcnt lgkmcnt(3)
	v_mfma_f32_32x32x16_bf16 v[16:31], v[248:251], v[200:203], v[16:31]
	ds_read2_b64 v[248:251], v252 offset0:100 offset1:102
	v_max3_f32 v0, v0, v107, v108
	v_max3_f32 v10, v14, v124, v125
	v_max3_f32 v0, v0, v109, v110
	v_max3_f32 v14, v10, v126, v127
	v_max3_f32 v0, v0, v111, v14
	v_mov_b32_e32 v14, v222
	s_waitcnt lgkmcnt(3)
	v_mfma_f32_32x32x16_bf16 v[64:79], v[234:237], v[196:199], v[64:79]
	ds_read2_b64 v[234:237], v231 offset0:8 offset1:10
	v_lshlrev_b32_e32 v14, 2, v14
	v_xor_b32_e32 v14, 0x80, v14
	ds_bpermute_b32 v14, v14, v0
	s_waitcnt lgkmcnt(0)
	v_max_f32_e32 v14, v14, v14
	v_max_f32_e32 v0, v0, v14
	v_cmp_lt_f32_e32 vcc, s53, v0
	s_cbranch_vccz .LBB0_1179
	v_max_f32_e32 v0, v0, v0
	v_max_f32_e32 v0, 0, v0
	v_add_f32_e32 v217, v217, v0
	v_pk_add_f32 v[96:97], v[96:97], v[0:1] op_sel_hi:[1,0] neg_lo:[0,1] neg_hi:[0,1]
	v_pk_add_f32 v[112:113], v[112:113], v[0:1] op_sel_hi:[1,0] neg_lo:[0,1] neg_hi:[0,1]
	v_pk_add_f32 v[98:99], v[98:99], v[0:1] op_sel_hi:[1,0] neg_lo:[0,1] neg_hi:[0,1]
	v_pk_add_f32 v[114:115], v[114:115], v[0:1] op_sel_hi:[1,0] neg_lo:[0,1] neg_hi:[0,1]
	v_pk_add_f32 v[100:101], v[100:101], v[0:1] op_sel_hi:[1,0] neg_lo:[0,1] neg_hi:[0,1]
	v_pk_add_f32 v[116:117], v[116:117], v[0:1] op_sel_hi:[1,0] neg_lo:[0,1] neg_hi:[0,1]
	v_pk_add_f32 v[102:103], v[102:103], v[0:1] op_sel_hi:[1,0] neg_lo:[0,1] neg_hi:[0,1]
	v_pk_add_f32 v[118:119], v[118:119], v[0:1] op_sel_hi:[1,0] neg_lo:[0,1] neg_hi:[0,1]
	v_pk_add_f32 v[104:105], v[104:105], v[0:1] op_sel_hi:[1,0] neg_lo:[0,1] neg_hi:[0,1]
	v_pk_add_f32 v[120:121], v[120:121], v[0:1] op_sel_hi:[1,0] neg_lo:[0,1] neg_hi:[0,1]
	v_pk_add_f32 v[106:107], v[106:107], v[0:1] op_sel_hi:[1,0] neg_lo:[0,1] neg_hi:[0,1]
	v_pk_add_f32 v[122:123], v[122:123], v[0:1] op_sel_hi:[1,0] neg_lo:[0,1] neg_hi:[0,1]
	v_pk_add_f32 v[108:109], v[108:109], v[0:1] op_sel_hi:[1,0] neg_lo:[0,1] neg_hi:[0,1]
	v_pk_add_f32 v[124:125], v[124:125], v[0:1] op_sel_hi:[1,0] neg_lo:[0,1] neg_hi:[0,1]
	v_pk_add_f32 v[110:111], v[110:111], v[0:1] op_sel_hi:[1,0] neg_lo:[0,1] neg_hi:[0,1]
	v_pk_add_f32 v[126:127], v[126:127], v[0:1] op_sel_hi:[1,0] neg_lo:[0,1] neg_hi:[0,1]
	v_exp_f32_e64 v0, -v0
	v_xor_b32_e32 v80, 0x80000000, v217
	v_mov_b32_e32 v81, v80
	v_mov_b32_e32 v82, v80
	v_mov_b32_e32 v83, v80
	v_mov_b32_e32 v84, v80
	v_mov_b32_e32 v85, v80
	v_mov_b32_e32 v86, v80
	v_mov_b32_e32 v87, v80
	v_mov_b32_e32 v88, v80
	v_mov_b32_e32 v89, v80
	v_mov_b32_e32 v90, v80
	v_mov_b32_e32 v91, v80
	v_mov_b32_e32 v92, v80
	v_mov_b32_e32 v93, v80
	v_mov_b32_e32 v94, v80
	v_mov_b32_e32 v95, v80
	s_branch .LBB0_1180

.LBB0_1180:
	v_mfma_f32_32x32x16_bf16 v[48:63], v[238:241], v[196:199], v[48:63]
	ds_read2_b64 v[238:241], v229 offset0:40 offset1:42
	v_exp_f32_e32 v220, v96
	v_exp_f32_e32 v221, v112
	v_exp_f32_e32 v14, v97
	v_exp_f32_e32 v15, v113
	v_mfma_f32_32x32x16_bf16 v[32:47], v[244:247], v[196:199], v[32:47]
	ds_read2_b64 v[244:247], v230 offset0:72 offset1:74
	v_exp_f32_e32 v12, v98
	v_exp_f32_e32 v13, v114
	v_exp_f32_e32 v10, v99
	v_exp_f32_e32 v11, v115
	v_mfma_f32_32x32x16_bf16 v[16:31], v[248:251], v[196:199], v[16:31]
	ds_read2_b64 v[248:251], v252 offset0:104 offset1:106
	v_exp_f32_e32 v98, v100
	v_exp_f32_e32 v99, v116
	v_exp_f32_e32 v96, v101
	v_exp_f32_e32 v97, v117
	v_mfma_f32_32x32x16_bf16 v[64:79], v[234:237], v[192:195], v[64:79]
	ds_read2_b64 v[234:237], v231 offset0:12 offset1:14
	v_exp_f32_e32 v112, v102
	v_exp_f32_e32 v113, v118
	v_exp_f32_e32 v100, v103
	v_exp_f32_e32 v101, v119
	s_waitcnt lgkmcnt(3)
	v_mfma_f32_32x32x16_bf16 v[48:63], v[238:241], v[192:195], v[48:63]
	ds_read2_b64 v[238:241], v229 offset0:44 offset1:46
	v_exp_f32_e32 v114, v104
	v_exp_f32_e32 v115, v120
	v_exp_f32_e32 v102, v105
	v_exp_f32_e32 v103, v121
	s_waitcnt lgkmcnt(3)
	v_mfma_f32_32x32x16_bf16 v[32:47], v[244:247], v[192:195], v[32:47]
	ds_read2_b64 v[244:247], v230 offset0:76 offset1:78
	v_exp_f32_e32 v116, v106
	v_exp_f32_e32 v117, v122
	v_exp_f32_e32 v104, v107
	v_exp_f32_e32 v105, v123
	s_waitcnt lgkmcnt(3)
	v_mfma_f32_32x32x16_bf16 v[16:31], v[248:251], v[192:195], v[16:31]
	ds_read2_b64 v[248:251], v252 offset0:108 offset1:110
	v_exp_f32_e32 v118, v108
	v_exp_f32_e32 v119, v124
	v_exp_f32_e32 v106, v109
	v_exp_f32_e32 v107, v125
	s_waitcnt lgkmcnt(3)
	v_mfma_f32_32x32x16_bf16 v[64:79], v[234:237], v[188:191], v[64:79]
	v_exp_f32_e32 v120, v110
	v_exp_f32_e32 v121, v126
	v_exp_f32_e32 v108, v111
	v_exp_f32_e32 v109, v127
	s_waitcnt lgkmcnt(2)
	v_mfma_f32_32x32x16_bf16 v[48:63], v[238:241], v[188:191], v[48:63]
	v_cvt_pk_bf16_f32 v200, v220, v14
	v_cvt_pk_bf16_f32 v201, v12, v10
	v_cvt_pk_bf16_f32 v202, v98, v96
	v_cvt_pk_bf16_f32 v203, v112, v100
	v_cvt_pk_bf16_f32 v196, v114, v102
	v_cvt_pk_bf16_f32 v197, v116, v104
	v_cvt_pk_bf16_f32 v198, v118, v106
	v_cvt_pk_bf16_f32 v199, v120, v108
	s_waitcnt lgkmcnt(1)
	v_mfma_f32_32x32x16_bf16 v[32:47], v[244:247], v[188:191], v[32:47]
	v_cvt_pk_bf16_f32 v192, v221, v15
	v_cvt_pk_bf16_f32 v193, v13, v11
	v_cvt_pk_bf16_f32 v194, v99, v97
	v_cvt_pk_bf16_f32 v195, v113, v101
	s_waitcnt lgkmcnt(0)
	v_mfma_f32_32x32x16_bf16 v[16:31], v[248:251], v[188:191], v[16:31]
	v_cvt_pk_bf16_f32 v188, v115, v103
	v_cvt_pk_bf16_f32 v189, v117, v105
	v_cvt_pk_bf16_f32 v190, v119, v107
	v_cvt_pk_bf16_f32 v191, v121, v109
	v_cmp_gt_f32_e32 vcc, 1.0, v0
	s_cbranch_vccz .LBB0_1182
	v_pk_mul_f32 v[78:79], v[0:1], v[78:79] op_sel_hi:[0,1]
	v_pk_mul_f32 v[76:77], v[0:1], v[76:77] op_sel_hi:[0,1]
	v_pk_mul_f32 v[74:75], v[0:1], v[74:75] op_sel_hi:[0,1]
	v_pk_mul_f32 v[72:73], v[0:1], v[72:73] op_sel_hi:[0,1]
	v_pk_mul_f32 v[70:71], v[0:1], v[70:71] op_sel_hi:[0,1]
	v_pk_mul_f32 v[68:69], v[0:1], v[68:69] op_sel_hi:[0,1]
	v_pk_mul_f32 v[66:67], v[0:1], v[66:67] op_sel_hi:[0,1]
	v_pk_mul_f32 v[64:65], v[0:1], v[64:65] op_sel_hi:[0,1]
	v_pk_mul_f32 v[62:63], v[0:1], v[62:63] op_sel_hi:[0,1]
	v_pk_mul_f32 v[60:61], v[0:1], v[60:61] op_sel_hi:[0,1]
	v_pk_mul_f32 v[58:59], v[0:1], v[58:59] op_sel_hi:[0,1]
	v_pk_mul_f32 v[56:57], v[0:1], v[56:57] op_sel_hi:[0,1]
	v_pk_mul_f32 v[54:55], v[0:1], v[54:55] op_sel_hi:[0,1]
	v_pk_mul_f32 v[52:53], v[0:1], v[52:53] op_sel_hi:[0,1]
	v_pk_mul_f32 v[50:51], v[0:1], v[50:51] op_sel_hi:[0,1]
	v_pk_mul_f32 v[48:49], v[0:1], v[48:49] op_sel_hi:[0,1]
	v_pk_mul_f32 v[46:47], v[0:1], v[46:47] op_sel_hi:[0,1]
	v_pk_mul_f32 v[44:45], v[0:1], v[44:45] op_sel_hi:[0,1]
	v_pk_mul_f32 v[42:43], v[0:1], v[42:43] op_sel_hi:[0,1]
	v_pk_mul_f32 v[40:41], v[0:1], v[40:41] op_sel_hi:[0,1]
	v_pk_mul_f32 v[38:39], v[0:1], v[38:39] op_sel_hi:[0,1]
	v_pk_mul_f32 v[36:37], v[0:1], v[36:37] op_sel_hi:[0,1]
	v_pk_mul_f32 v[34:35], v[0:1], v[34:35] op_sel_hi:[0,1]
	v_pk_mul_f32 v[32:33], v[0:1], v[32:33] op_sel_hi:[0,1]
	v_pk_mul_f32 v[30:31], v[0:1], v[30:31] op_sel_hi:[0,1]
	v_pk_mul_f32 v[28:29], v[0:1], v[28:29] op_sel_hi:[0,1]
	v_pk_mul_f32 v[26:27], v[0:1], v[26:27] op_sel_hi:[0,1]
	v_pk_mul_f32 v[24:25], v[0:1], v[24:25] op_sel_hi:[0,1]
	v_pk_mul_f32 v[22:23], v[0:1], v[22:23] op_sel_hi:[0,1]
	v_pk_mul_f32 v[20:21], v[0:1], v[20:21] op_sel_hi:[0,1]
	v_pk_mul_f32 v[18:19], v[0:1], v[18:19] op_sel_hi:[0,1]
	v_pk_mul_f32 v[16:17], v[0:1], v[16:17] op_sel_hi:[0,1]

; #define LAS __attribute__((address_space(3)))
; __global__ void __launch_bounds__(NTHREADS, 2) fwd_kernel(Params p) {
;     extern __shared__ __attribute__((aligned(16))) unsigned char lds_raw[];
;     LAS unsigned char* lds = (LAS unsigned char*)lds_raw;
;     const int G = gridDim.x, bx = blockIdx.x;
;     const int wv = __builtin_amdgcn_readfirstlane((int)threadIdx.x >> 6);
	.amdhsa_kernel _Z10fwd_kernel6Params
		.amdhsa_group_segment_fixed_size 0
		.amdhsa_private_segment_fixed_size 0
		.amdhsa_kernarg_size 560
		.amdhsa_user_sgpr_count 2
		.amdhsa_user_sgpr_dispatch_ptr 0
		.amdhsa_user_sgpr_queue_ptr 0
		.amdhsa_user_sgpr_kernarg_segment_ptr 1
		.amdhsa_user_sgpr_dispatch_id 0
		.amdhsa_user_sgpr_kernarg_preload_length 0
		.amdhsa_user_sgpr_kernarg_preload_offset 0
		.amdhsa_user_sgpr_private_segment_size 0
		.amdhsa_uses_dynamic_stack 0
		.amdhsa_enable_private_segment 0
		.amdhsa_system_sgpr_workgroup_id_x 1
		.amdhsa_system_sgpr_workgroup_id_y 0
		.amdhsa_system_sgpr_workgroup_id_z 0
		.amdhsa_system_sgpr_workgroup_info 0
		.amdhsa_system_vgpr_workitem_id 2
		.amdhsa_next_free_vgpr 255
		.amdhsa_next_free_sgpr 102
		.amdhsa_accum_offset 256
		.amdhsa_reserve_vcc 1
		.amdhsa_float_round_mode_32 0
		.amdhsa_float_round_mode_16_64 0
		.amdhsa_float_denorm_mode_32 3
		.amdhsa_float_denorm_mode_16_64 3
		.amdhsa_dx10_clamp 1
		.amdhsa_ieee_mode 1
		.amdhsa_fp16_overflow 0
		.amdhsa_tg_split 0
		.amdhsa_exception_fp_ieee_invalid_op 0
		.amdhsa_exception_fp_denorm_src 0
		.amdhsa_exception_fp_ieee_div_zero 0
		.amdhsa_exception_fp_ieee_overflow 0
		.amdhsa_exception_fp_ieee_underflow 0
		.amdhsa_exception_fp_ieee_inexact 0
		.amdhsa_exception_int_div_zero 0
	.end_amdhsa_kernel

; __global__ void __launch_bounds__(NTHREADS, 2) fwd_kernel(Params p) {
amdhsa.kernels:
  - .agpr_count:     0
    .args:
      - .offset:         0
        .size:           304
        .value_kind:     by_value
      - .offset:         304
        .size:           4
        .value_kind:     hidden_block_count_x
      - .offset:         308
        .size:           4
        .value_kind:     hidden_block_count_y
      - .offset:         312
        .size:           4
        .value_kind:     hidden_block_count_z
      - .offset:         316
        .size:           2
        .value_kind:     hidden_group_size_x
      - .offset:         318
        .size:           2
        .value_kind:     hidden_group_size_y
      - .offset:         320
        .size:           2
        .value_kind:     hidden_group_size_z
      - .offset:         322
        .size:           2
        .value_kind:     hidden_remainder_x
      - .offset:         324
        .size:           2
        .value_kind:     hidden_remainder_y
      - .offset:         326
        .size:           2
        .value_kind:     hidden_remainder_z
      - .offset:         344
        .size:           8
        .value_kind:     hidden_global_offset_x
      - .offset:         352
        .size:           8
        .value_kind:     hidden_global_offset_y
      - .offset:         360
        .size:           8
        .value_kind:     hidden_global_offset_z
      - .offset:         368
        .size:           2
        .value_kind:     hidden_grid_dims
      - .offset:         392
        .size:           8
        .value_kind:     hidden_multigrid_sync_arg
      - .offset:         424
        .size:           4
        .value_kind:     hidden_dynamic_lds_size
    .group_segment_fixed_size: 0
    .kernarg_segment_align: 8
    .kernarg_segment_size: 560
    .language:       OpenCL C
    .language_version:
      - 2
      - 0
    .max_flat_workgroup_size: 512
    .name:           _Z10fwd_kernel6Params
    .private_segment_fixed_size: 0
    .sgpr_count:     108
    .sgpr_spill_count: 34
    .symbol:         _Z10fwd_kernel6Params.kd
    .uniform_work_group_size: 1
    .uses_dynamic_stack: false
    .vgpr_count:     255
    .vgpr_spill_count: 0
    .wavefront_size: 64
